# attnA: P.V MFMAs in k-step-major order spread evenly under exp2/pack/sum VALU work (only 4 P.V MFMAs before the softmax)
# speedup vs baseline: 1.0018x; 1.0018x over previous
; #define LAS __attribute__((address_space(3)))
; __device__ __forceinline__ float fexp2(float x) { return __builtin_amdgcn_exp2f(x); }
; #define MFMA32(a, b, c) __builtin_amdgcn_mfma_f32_32x32x16_bf16((a), (b), (c), 0, 0, 0)
; __device__ __forceinline__ bf16x8 v_build(const VRaw& r, int ks) { return (bf16x8){r.lo[ks][0], r.lo[ks][1], r.lo[ks][2], r.lo[ks][3], r.hv[ks][0], r.hv[ks][1], r.hv[ks][2], r.hv[ks][3]}; }
; #define SB_ __builtin_amdgcn_sched_barrier(0)
; __device__ __forceinline__ void attnA_unit(const P2Ctx& C, int b, int h, int qb) {
;     ...
;             A_QK(kt)
;             if (!(pf & 4)) {
;             const LAS unsigned char* vimg = lds + ((kt - 1) & 3) * 32768 + 16384;
;             VRaw va;
;             v_issue<4>(vimg, 0, lane, va);
;             A_MAX()
;             float fres = 1.0f; bool resc = false;
;             if (__any(mx > ATHR)) {
;                 const float dl = fmaxf(mx, 0.f);
;                 mhat += dl;
;                 fres = fexp2(-dl); resc = true;
; #pragma unroll
;                 for (int kb2 = 0; kb2 < 2; ++kb2)
; #pragma unroll
;                     for (int r = 0; r < 16; ++r) s[kb2][r] -= dl;
;             }
;             float ps = 0.f;
;             v_wait(va);
;             __builtin_amdgcn_s_setprio(1);
; #pragma unroll
;             for (int ks = 0; ks < 4; ++ks) o[0] = MFMA32(v_build(va, ks), pf_[ks], o[0]);
;             EX4_(s[0], 0); EX4_(s[0], 4); EX4_(s[0], 8); EX4_(s[0], 12);
;             SB_; v_issue<4>(vimg, 1, lane, va); v_wait(va);
; #pragma unroll
;             for (int ks = 0; ks < 4; ++ks) o[1] = MFMA32(v_build(va, ks), pf_[ks], o[1]);
;             EX4_(s[1], 0); EX4_(s[1], 4); EX4_(s[1], 8); EX4_(s[1], 12);
;             SB_; v_issue<4>(vimg, 2, lane, va); v_wait(va);
; #pragma unroll
;             for (int ks = 0; ks < 4; ++ks) o[2] = MFMA32(v_build(va, ks), pf_[ks], o[2]);
;             SUM8_(s[0], 0); SUM8_(s[0], 8); SUM8_(s[1], 0); SUM8_(s[1], 8);
;             SB_; v_issue<4>(vimg, 3, lane, va); v_wait(va);
;             o[3] = MFMA32(v_build(va, 0), pf_[0], o[3]); pf_[0] = pack_p(s[0], 0);
;             o[3] = MFMA32(v_build(va, 1), pf_[1], o[3]); pf_[1] = pack_p(s[0], 1);
;             o[3] = MFMA32(v_build(va, 2), pf_[2], o[3]); pf_[2] = pack_p(s[1], 0);
;             o[3] = MFMA32(v_build(va, 3), pf_[3], o[3]); pf_[3] = pack_p(s[1], 1);
.LaA_nodma_7:
	s_waitcnt lgkmcnt(7)
	v_mfma_f32_32x32x16_bf16 v[68:83], v[100:103], v[164:167], v[220:235]
	ds_read_b64_tr_b16 v[132:133], v237 offset:0
	ds_read_b64_tr_b16 v[134:135], v237 offset:2048
	s_waitcnt lgkmcnt(8)
	v_mfma_f32_32x32x16_bf16 v[84:99], v[104:107], v[164:167], v[220:235]
	ds_read_b64_tr_b16 v[136:137], v237 offset:512
	ds_read_b64_tr_b16 v[138:139], v237 offset:2560
	s_waitcnt lgkmcnt(9)
	v_mfma_f32_32x32x16_bf16 v[68:83], v[108:111], v[168:171], v[68:83]
	ds_read_b64_tr_b16 v[140:141], v237 offset:1024
	ds_read_b64_tr_b16 v[142:143], v237 offset:3072
	s_waitcnt lgkmcnt(10)
	v_mfma_f32_32x32x16_bf16 v[84:99], v[112:115], v[168:171], v[84:99]
	ds_read_b64_tr_b16 v[144:145], v237 offset:1536
	ds_read_b64_tr_b16 v[146:147], v237 offset:3584
	s_waitcnt lgkmcnt(11)
	v_mfma_f32_32x32x16_bf16 v[68:83], v[116:119], v[172:175], v[68:83]
	s_waitcnt lgkmcnt(10)
	v_mfma_f32_32x32x16_bf16 v[84:99], v[120:123], v[172:175], v[84:99]
	s_waitcnt lgkmcnt(9)
	v_mfma_f32_32x32x16_bf16 v[68:83], v[124:127], v[176:179], v[68:83]
	s_waitcnt lgkmcnt(8)
	v_mfma_f32_32x32x16_bf16 v[84:99], v[128:131], v[176:179], v[84:99]
	s_waitcnt lgkmcnt(0)
	ds_read_b64_tr_b16 v[148:149], v237 offset:4096
	ds_read_b64_tr_b16 v[150:151], v237 offset:6144
	v_mfma_f32_32x32x16_bf16 v[4:19], v[132:135], v[180:183], v[4:19]
	ds_read_b64_tr_b16 v[152:153], v237 offset:4608
	ds_read_b64_tr_b16 v[154:155], v237 offset:6656
	ds_read_b64_tr_b16 v[156:157], v237 offset:5120
	v_mfma_f32_32x32x16_bf16 v[20:35], v[136:139], v[180:183], v[20:35]
	ds_read_b64_tr_b16 v[158:159], v237 offset:7168
	ds_read_b64_tr_b16 v[160:161], v237 offset:5632
	ds_read_b64_tr_b16 v[162:163], v237 offset:7680
	s_lshl_b32 s6, s14, 6
	s_cmp_gt_i32 s6, s26
	s_cbranch_scc1 .LaA_near_8
.LaA_far_9:
	v_mfma_f32_32x32x16_bf16 v[36:51], v[140:143], v[180:183], v[36:51]
	v_max_f32_e32 v242, v68, v69
	v_max_f32_e32 v243, v84, v85
	v_max3_f32 v242, v242, v70, v71
	v_max3_f32 v243, v243, v86, v87
	v_max3_f32 v242, v242, v72, v73
	v_max3_f32 v243, v243, v88, v89
	v_max3_f32 v242, v242, v74, v75
	v_max3_f32 v243, v243, v90, v91
	v_max3_f32 v242, v242, v76, v77
	v_mfma_f32_32x32x16_bf16 v[52:67], v[144:147], v[180:183], v[52:67]
	v_max3_f32 v243, v243, v92, v93
	v_max3_f32 v242, v242, v78, v79
	v_max3_f32 v243, v243, v94, v95
	v_max3_f32 v242, v242, v80, v81
	v_max3_f32 v243, v243, v96, v97
	v_max3_f32 v242, v242, v82, v83
	v_max3_f32 v243, v243, v98, v99
	v_max_f32_e32 v242, v242, v243
	v_mov_b32_e32 v243, v242
	s_nop 1
	v_permlane32_swap_b32 v243, v242
	v_max_f32_e32 v247, v243, v242
	v_cmp_lt_f32_e32 vcc, 0x41000000, v247
	s_cmp_lg_u64 vcc, 0
	s_cbranch_scc1 .LaA_resc_pre
.LaA_resc_back:
	s_waitcnt lgkmcnt(0)
	ds_read_b64_tr_b16 v[132:133], v237 offset:8192
	ds_read_b64_tr_b16 v[134:135], v237 offset:10240
	v_mfma_f32_32x32x16_bf16 v[4:19], v[148:151], v[184:187], v[4:19]
	ds_read_b64_tr_b16 v[136:137], v237 offset:8704
	ds_read_b64_tr_b16 v[138:139], v237 offset:10752
	ds_read_b64_tr_b16 v[140:141], v237 offset:9216
	v_exp_f32_e32 v68, v68
	v_exp_f32_e32 v69, v69
	v_exp_f32_e32 v70, v70
	v_exp_f32_e32 v71, v71
	v_mfma_f32_32x32x16_bf16 v[20:35], v[152:155], v[184:187], v[20:35]
	ds_read_b64_tr_b16 v[142:143], v237 offset:11264
	ds_read_b64_tr_b16 v[144:145], v237 offset:9728
	ds_read_b64_tr_b16 v[146:147], v237 offset:11776
	v_exp_f32_e32 v72, v72
	v_exp_f32_e32 v73, v73
	v_exp_f32_e32 v74, v74
	v_exp_f32_e32 v75, v75
	v_mfma_f32_32x32x16_bf16 v[36:51], v[156:159], v[184:187], v[36:51]
	v_exp_f32_e32 v76, v76
	v_exp_f32_e32 v77, v77
	v_exp_f32_e32 v78, v78
	v_exp_f32_e32 v79, v79
	v_cvt_pk_bf16_f32 v180, v68, v69
	v_cvt_pk_bf16_f32 v181, v70, v71
	v_mfma_f32_32x32x16_bf16 v[52:67], v[160:163], v[184:187], v[52:67]
	v_exp_f32_e32 v80, v80
	v_exp_f32_e32 v81, v81
	v_exp_f32_e32 v82, v82
	v_exp_f32_e32 v83, v83
	v_cvt_pk_bf16_f32 v182, v72, v73
	v_cvt_pk_bf16_f32 v183, v74, v75
	s_waitcnt lgkmcnt(0)
	ds_read_b64_tr_b16 v[148:149], v237 offset:12288
	ds_read_b64_tr_b16 v[150:151], v237 offset:14336
	v_mfma_f32_32x32x16_bf16 v[4:19], v[132:135], v[188:191], v[4:19]
	ds_read_b64_tr_b16 v[152:153], v237 offset:12800
	ds_read_b64_tr_b16 v[154:155], v237 offset:14848
	ds_read_b64_tr_b16 v[156:157], v237 offset:13312
	v_exp_f32_e32 v84, v84
	v_exp_f32_e32 v85, v85
	v_exp_f32_e32 v86, v86
	v_exp_f32_e32 v87, v87
	v_cvt_pk_bf16_f32 v184, v76, v77
	v_cvt_pk_bf16_f32 v185, v78, v79
	v_mfma_f32_32x32x16_bf16 v[20:35], v[136:139], v[188:191], v[20:35]
	ds_read_b64_tr_b16 v[158:159], v237 offset:15360
	ds_read_b64_tr_b16 v[160:161], v237 offset:13824
	ds_read_b64_tr_b16 v[162:163], v237 offset:15872
	v_exp_f32_e32 v88, v88
	v_exp_f32_e32 v89, v89
	v_exp_f32_e32 v90, v90
	v_exp_f32_e32 v91, v91
	v_cvt_pk_bf16_f32 v186, v80, v81
	v_cvt_pk_bf16_f32 v187, v82, v83
	v_mfma_f32_32x32x16_bf16 v[36:51], v[140:143], v[188:191], v[36:51]
	v_exp_f32_e32 v92, v92
	v_exp_f32_e32 v93, v93
	v_exp_f32_e32 v94, v94
	v_exp_f32_e32 v95, v95
	v_add_f32_e32 v245, v68, v69
	v_add_f32_e32 v243, v70, v71
	v_add_f32_e32 v245, v245, v243
	v_add_f32_e32 v243, v72, v73
	v_mfma_f32_32x32x16_bf16 v[52:67], v[144:147], v[188:191], v[52:67]
	v_exp_f32_e32 v96, v96
	v_exp_f32_e32 v97, v97
	v_exp_f32_e32 v98, v98
	v_exp_f32_e32 v99, v99
	v_add_f32_e32 v242, v74, v75
	v_add_f32_e32 v243, v243, v242
	v_add_f32_e32 v245, v245, v243
	v_add_f32_e32 v246, v76, v77
	s_waitcnt lgkmcnt(0)
	v_mfma_f32_32x32x16_bf16 v[4:19], v[148:151], v[192:195], v[4:19]
	v_cvt_pk_bf16_f32 v188, v84, v85
	v_cvt_pk_bf16_f32 v189, v86, v87
	v_cvt_pk_bf16_f32 v190, v88, v89
	v_cvt_pk_bf16_f32 v191, v90, v91
	v_add_f32_e32 v243, v78, v79
	v_add_f32_e32 v246, v246, v243
	v_add_f32_e32 v243, v80, v81
	v_add_f32_e32 v242, v82, v83
	v_add_f32_e32 v243, v243, v242
	v_add_f32_e32 v246, v246, v243
	v_add_f32_e32 v245, v245, v246
	v_mfma_f32_32x32x16_bf16 v[20:35], v[152:155], v[192:195], v[20:35]
	v_add_f32_e32 v246, v84, v85
	v_add_f32_e32 v243, v86, v87
	v_add_f32_e32 v246, v246, v243
	v_add_f32_e32 v243, v88, v89
	v_add_f32_e32 v242, v90, v91
	v_add_f32_e32 v243, v243, v242
	v_mfma_f32_32x32x16_bf16 v[36:51], v[156:159], v[192:195], v[36:51]
	v_add_f32_e32 v246, v246, v243
	v_add_f32_e32 v245, v245, v246
	v_add_f32_e32 v246, v92, v93
	v_add_f32_e32 v243, v94, v95
	v_add_f32_e32 v246, v246, v243
	v_mfma_f32_32x32x16_bf16 v[52:67], v[160:163], v[192:195], v[52:67]
	v_add_f32_e32 v243, v96, v97
	v_add_f32_e32 v242, v98, v99
	v_add_f32_e32 v243, v243, v242
	v_add_f32_e32 v246, v246, v243
	v_add_f32_e32 v245, v245, v246
	v_cvt_pk_bf16_f32 v192, v92, v93
	v_cvt_pk_bf16_f32 v193, v94, v95
	v_cvt_pk_bf16_f32 v194, v96, v97
	v_cvt_pk_bf16_f32 v195, v98, v99
	s_cmp_lg_u32 s25, 0
	s_cbranch_scc1 .LaA_resc_post
